# FFN-up tiles: accumulators not zeroed (64 v_mov removed); the first four MFMAs of a tile take C=0 (one peeled loop body)
# baseline (speedup 1.0000x reference)
.LBB0_669:
	s_or_b64 exec, exec, s[18:19]
	v_add_co_u32_e32 v4, vcc, 0x7000, v30
	s_mul_i32 s18, s52, 62
	s_nop 0
	v_addc_co_u32_e32 v5, vcc, 0, v31, vcc
	global_load_dwordx4 v[110:113], v[4:5], off
	v_ashrrev_i32_e32 v4, 3, v41
	s_add_i32 s18, s3, s18
	v_lshrrev_b32_e32 v116, 4, v4
	s_add_i32 s18, s18, s51
	v_ashrrev_i32_e32 v8, 3, v40
	v_lshlrev_b64 v[4:5], 18, v[116:117]
	s_lshl_b32 s18, s18, 1
	v_lshl_add_u64 v[2:3], v[2:3], 1, v[4:5]
	v_lshrrev_b32_e32 v116, 4, v8
	v_subrev_u16_e32 v4, s18, v163
	v_ashrrev_i32_e32 v7, 3, v39
	v_lshl_add_u64 v[128:129], v[122:123], 0, v[2:3]
	v_lshlrev_b64 v[2:3], 18, v[116:117]
	v_and_b32_e32 v4, 0x7f, v4
	s_waitcnt lgkmcnt(0)
	s_barrier
	ds_read_b128 v[102:105], v168 offset:18432
	ds_read_b128 v[94:97], v168 offset:23040
	ds_read_b128 v[106:109], v169
	ds_read_b128 v[98:101], v169 offset:4608
	v_lshl_or_b32 v2, v4, 7, v2
	v_lshrrev_b32_e32 v116, 4, v7
	v_subrev_u16_e32 v4, s18, v164
	v_ashrrev_i32_e32 v6, 3, v38
	v_lshl_add_u64 v[130:131], v[122:123], 0, v[2:3]
	v_lshlrev_b64 v[2:3], 18, v[116:117]
	v_and_b32_e32 v4, 0x7f, v4
	v_lshl_or_b32 v2, v4, 7, v2
	v_lshrrev_b32_e32 v116, 4, v6
	v_subrev_u16_e32 v4, s18, v165
	v_lshl_add_u64 v[132:133], v[122:123], 0, v[2:3]
	v_lshlrev_b64 v[2:3], 18, v[116:117]
	v_and_b32_e32 v4, 0x7f, v4
	v_lshl_or_b32 v2, v4, 7, v2
	v_lshl_add_u64 v[134:135], v[122:123], 0, v[2:3]
	s_mov_b32 s15, 0
	v_lshl_add_u64 v[136:137], v[124:125], 0, s[16:17]
	s_mov_b64 s[16:17], 0
	s_sub_u32 s62, 0x102c000, s34
	v_add_u32_e32 v220, s62, v136
	s_sub_u32 s62, 0x102d000, s34
	v_add_u32_e32 v221, s62, v136
	s_sub_u32 s62, 0x102e000, s34
	v_add_u32_e32 v222, s62, v136
	s_sub_u32 s62, 0x102f000, s34
	v_add_u32_e32 v223, s62, v136
	v_subrev_u32_e32 v224, s34, v134
	v_subrev_u32_e32 v225, s34, v132
	v_subrev_u32_e32 v226, s34, v130
	v_subrev_u32_e32 v227, s34, v128
	s_mov_b32 s64, s34
	s_mov_b32 s65, s35
	s_mov_b32 s66, 6
	ds_read_b128 v[172:175], v168 offset:18464
	ds_read_b128 v[176:179], v168 offset:23072
	ds_read_b128 v[180:183], v169 offset:32
	ds_read_b128 v[184:187], v169 offset:4640
	s_waitcnt lgkmcnt(4)
	v_mfma_f32_32x32x16_bf16 v[50:65], v[102:105], v[106:109], 0
	s_waitcnt vmcnt(7)
	ds_write_b128 v140, v[66:69] offset:36864
	v_mfma_f32_32x32x16_bf16 v[34:49], v[94:97], v[106:109], 0
	s_waitcnt vmcnt(6)
	ds_write_b128 v140, v[74:77] offset:55296
	v_mfma_f32_32x32x16_bf16 v[18:33], v[102:105], v[98:101], 0
	s_waitcnt vmcnt(5)
	ds_write_b128 v142, v[70:73] offset:36864
	v_mfma_f32_32x32x16_bf16 v[2:17], v[94:97], v[98:101], 0
	s_waitcnt vmcnt(4)
	ds_write_b128 v142, v[82:85] offset:55296
	ds_read_b128 v[102:105], v168 offset:18496
	ds_read_b128 v[94:97], v168 offset:23104
	ds_read_b128 v[106:109], v169 offset:64
	ds_read_b128 v[98:101], v169 offset:4672
	s_waitcnt lgkmcnt(4)
	v_mfma_f32_32x32x16_bf16 v[50:65], v[172:175], v[180:183], v[50:65]
	s_waitcnt vmcnt(3)
	ds_write_b128 v144, v[78:81] offset:36864
	v_mfma_f32_32x32x16_bf16 v[34:49], v[176:179], v[180:183], v[34:49]
	s_waitcnt vmcnt(2)
	ds_write_b128 v144, v[86:89] offset:55296
	v_mfma_f32_32x32x16_bf16 v[18:33], v[172:175], v[184:187], v[18:33]
	s_waitcnt vmcnt(1)
	ds_write_b128 v146, v[90:93] offset:36864
	v_mfma_f32_32x32x16_bf16 v[2:17], v[176:179], v[184:187], v[2:17]
	s_waitcnt vmcnt(0)
	ds_write_b128 v146, v[110:113] offset:55296
	ds_read_b128 v[172:175], v168 offset:18528
	ds_read_b128 v[176:179], v168 offset:23136
	ds_read_b128 v[180:183], v169 offset:96
	ds_read_b128 v[184:187], v169 offset:4704
	s_waitcnt lgkmcnt(8)
	v_mfma_f32_32x32x16_bf16 v[50:65], v[102:105], v[106:109], v[50:65]
	s_mov_b64 exec, s[4:5]
	global_load_dwordx4 v[66:69], v224, s[64:65]
	s_mov_b64 exec, -1
	global_load_dwordx4 v[74:77], v220, s[64:65]
	v_mfma_f32_32x32x16_bf16 v[34:49], v[94:97], v[106:109], v[34:49]
	s_mov_b64 exec, s[6:7]
	global_load_dwordx4 v[70:73], v225, s[64:65]
	s_mov_b64 exec, -1
	global_load_dwordx4 v[82:85], v221, s[64:65]
	v_mfma_f32_32x32x16_bf16 v[18:33], v[102:105], v[98:101], v[18:33]
	s_mov_b64 exec, s[8:9]
	global_load_dwordx4 v[78:81], v226, s[64:65]
	s_mov_b64 exec, -1
	global_load_dwordx4 v[86:89], v222, s[64:65]
	v_mfma_f32_32x32x16_bf16 v[2:17], v[94:97], v[98:101], v[2:17]
	s_mov_b64 exec, s[10:11]
	global_load_dwordx4 v[90:93], v227, s[64:65]
	s_mov_b64 exec, -1
	global_load_dwordx4 v[110:113], v223, s[64:65]
	s_add_u32 s64, s64, 0x4000
	s_addc_u32 s65, s65, 0
	s_waitcnt lgkmcnt(0)
	s_barrier
	ds_read_b128 v[102:105], v168 offset:55296
	ds_read_b128 v[94:97], v168 offset:59904
	ds_read_b128 v[106:109], v169 offset:36864
	ds_read_b128 v[98:101], v169 offset:41472
	v_mfma_f32_32x32x16_bf16 v[50:65], v[172:175], v[180:183], v[50:65]
	v_mfma_f32_32x32x16_bf16 v[34:49], v[176:179], v[180:183], v[34:49]
	v_mfma_f32_32x32x16_bf16 v[18:33], v[172:175], v[184:187], v[18:33]
	v_mfma_f32_32x32x16_bf16 v[2:17], v[176:179], v[184:187], v[2:17]
	ds_read_b128 v[172:175], v168 offset:55328
	ds_read_b128 v[176:179], v168 offset:59936
	ds_read_b128 v[180:183], v169 offset:36896
	ds_read_b128 v[184:187], v169 offset:41504
	s_waitcnt lgkmcnt(4)
	v_mfma_f32_32x32x16_bf16 v[50:65], v[102:105], v[106:109], v[50:65]
	s_waitcnt vmcnt(7)
	ds_write_b128 v140, v[66:69]
	v_mfma_f32_32x32x16_bf16 v[34:49], v[94:97], v[106:109], v[34:49]
	s_waitcnt vmcnt(6)
	ds_write_b128 v140, v[74:77] offset:18432
	v_mfma_f32_32x32x16_bf16 v[18:33], v[102:105], v[98:101], v[18:33]
	s_waitcnt vmcnt(5)
	ds_write_b128 v142, v[70:73]
	v_mfma_f32_32x32x16_bf16 v[2:17], v[94:97], v[98:101], v[2:17]
	s_waitcnt vmcnt(4)
	ds_write_b128 v142, v[82:85] offset:18432
	ds_read_b128 v[102:105], v168 offset:55360
	ds_read_b128 v[94:97], v168 offset:59968
	ds_read_b128 v[106:109], v169 offset:36928
	ds_read_b128 v[98:101], v169 offset:41536
	s_waitcnt lgkmcnt(4)
	v_mfma_f32_32x32x16_bf16 v[50:65], v[172:175], v[180:183], v[50:65]
	s_waitcnt vmcnt(3)
	ds_write_b128 v144, v[78:81]
	v_mfma_f32_32x32x16_bf16 v[34:49], v[176:179], v[180:183], v[34:49]
	s_waitcnt vmcnt(2)
	ds_write_b128 v144, v[86:89] offset:18432
	v_mfma_f32_32x32x16_bf16 v[18:33], v[172:175], v[184:187], v[18:33]
	s_waitcnt vmcnt(1)
	ds_write_b128 v146, v[90:93]
	v_mfma_f32_32x32x16_bf16 v[2:17], v[176:179], v[184:187], v[2:17]
	s_waitcnt vmcnt(0)
	ds_write_b128 v146, v[110:113] offset:18432
	ds_read_b128 v[172:175], v168 offset:55392
	ds_read_b128 v[176:179], v168 offset:60000
	ds_read_b128 v[180:183], v169 offset:36960
	ds_read_b128 v[184:187], v169 offset:41568
	s_waitcnt lgkmcnt(8)
	v_mfma_f32_32x32x16_bf16 v[50:65], v[102:105], v[106:109], v[50:65]
	s_mov_b64 exec, s[4:5]
	global_load_dwordx4 v[66:69], v224, s[64:65]
	s_mov_b64 exec, -1
	global_load_dwordx4 v[74:77], v220, s[64:65]
	v_mfma_f32_32x32x16_bf16 v[34:49], v[94:97], v[106:109], v[34:49]
	s_mov_b64 exec, s[6:7]
	global_load_dwordx4 v[70:73], v225, s[64:65]
	s_mov_b64 exec, -1
	global_load_dwordx4 v[82:85], v221, s[64:65]
	v_mfma_f32_32x32x16_bf16 v[18:33], v[102:105], v[98:101], v[18:33]
	s_mov_b64 exec, s[8:9]
	global_load_dwordx4 v[78:81], v226, s[64:65]
	s_mov_b64 exec, -1
	global_load_dwordx4 v[86:89], v222, s[64:65]
	v_mfma_f32_32x32x16_bf16 v[2:17], v[94:97], v[98:101], v[2:17]
	s_mov_b64 exec, s[10:11]
	global_load_dwordx4 v[90:93], v227, s[64:65]
	s_mov_b64 exec, -1
	global_load_dwordx4 v[110:113], v223, s[64:65]
	s_add_u32 s64, s64, 0x4000
	s_addc_u32 s65, s65, 0
	s_waitcnt lgkmcnt(0)
	s_barrier
	ds_read_b128 v[102:105], v168 offset:18432
	ds_read_b128 v[94:97], v168 offset:23040
	ds_read_b128 v[106:109], v169
	ds_read_b128 v[98:101], v169 offset:4608
	v_mfma_f32_32x32x16_bf16 v[50:65], v[172:175], v[180:183], v[50:65]
	v_mfma_f32_32x32x16_bf16 v[34:49], v[176:179], v[180:183], v[34:49]
	v_mfma_f32_32x32x16_bf16 v[18:33], v[172:175], v[184:187], v[18:33]
	v_mfma_f32_32x32x16_bf16 v[2:17], v[176:179], v[184:187], v[2:17]

.LBB0_2386:
	s_or_b64 exec, exec, s[22:23]
	v_add_co_u32_e32 v4, vcc, 0x7000, v30
	s_mul_i32 s22, s38, 62
	s_nop 0
	v_addc_co_u32_e32 v5, vcc, 0, v31, vcc
	global_load_dwordx4 v[110:113], v[4:5], off
	v_ashrrev_i32_e32 v4, 3, v41
	s_add_i32 s22, s24, s22
	v_lshrrev_b32_e32 v116, 4, v4
	s_add_i32 s22, s22, s37
	v_ashrrev_i32_e32 v8, 3, v40
	v_lshlrev_b64 v[4:5], 18, v[116:117]
	s_lshl_b32 s22, s22, 1
	v_lshl_add_u64 v[2:3], v[2:3], 1, v[4:5]
	v_lshrrev_b32_e32 v116, 4, v8
	v_subrev_u16_e32 v4, s22, v163
	v_ashrrev_i32_e32 v7, 3, v39
	v_lshl_add_u64 v[128:129], v[122:123], 0, v[2:3]
	v_lshlrev_b64 v[2:3], 18, v[116:117]
	v_and_b32_e32 v4, 0x7f, v4
	s_waitcnt lgkmcnt(0)
	s_barrier
	ds_read_b128 v[102:105], v168 offset:18432
	ds_read_b128 v[94:97], v168 offset:23040
	ds_read_b128 v[106:109], v169
	ds_read_b128 v[98:101], v169 offset:4608
	v_lshl_or_b32 v2, v4, 7, v2
	v_lshrrev_b32_e32 v116, 4, v7
	v_subrev_u16_e32 v4, s22, v164
	v_ashrrev_i32_e32 v6, 3, v38
	v_lshl_add_u64 v[130:131], v[122:123], 0, v[2:3]
	v_lshlrev_b64 v[2:3], 18, v[116:117]
	v_and_b32_e32 v4, 0x7f, v4
	v_lshl_or_b32 v2, v4, 7, v2
	v_lshrrev_b32_e32 v116, 4, v6
	v_subrev_u16_e32 v4, s22, v165
	v_lshl_add_u64 v[132:133], v[122:123], 0, v[2:3]
	v_lshlrev_b64 v[2:3], 18, v[116:117]
	v_and_b32_e32 v4, 0x7f, v4
	v_lshl_or_b32 v2, v4, 7, v2
	v_lshl_add_u64 v[134:135], v[122:123], 0, v[2:3]
	s_mov_b32 s19, 0
	v_lshl_add_u64 v[136:137], v[124:125], 0, s[20:21]
	s_mov_b64 s[20:21], 0
	s_sub_u32 s62, 0x1b2c000, s34
	v_add_u32_e32 v220, s62, v136
	s_sub_u32 s62, 0x1b2d000, s34
	v_add_u32_e32 v221, s62, v136
	s_sub_u32 s62, 0x1b2e000, s34
	v_add_u32_e32 v222, s62, v136
	s_sub_u32 s62, 0x1b2f000, s34
	v_add_u32_e32 v223, s62, v136
	v_subrev_u32_e32 v224, s34, v134
	v_subrev_u32_e32 v225, s34, v132
	v_subrev_u32_e32 v226, s34, v130
	v_subrev_u32_e32 v227, s34, v128
	s_mov_b32 s64, s34
	s_mov_b32 s65, s35
	s_mov_b32 s66, 6
	ds_read_b128 v[172:175], v168 offset:18464
	ds_read_b128 v[176:179], v168 offset:23072
	ds_read_b128 v[180:183], v169 offset:32
	ds_read_b128 v[184:187], v169 offset:4640
	s_waitcnt lgkmcnt(4)
	v_mfma_f32_32x32x16_bf16 v[50:65], v[102:105], v[106:109], 0
	s_waitcnt vmcnt(7)
	ds_write_b128 v140, v[66:69] offset:36864
	v_mfma_f32_32x32x16_bf16 v[34:49], v[94:97], v[106:109], 0
	s_waitcnt vmcnt(6)
	ds_write_b128 v140, v[74:77] offset:55296
	v_mfma_f32_32x32x16_bf16 v[18:33], v[102:105], v[98:101], 0
	s_waitcnt vmcnt(5)
	ds_write_b128 v142, v[70:73] offset:36864
	v_mfma_f32_32x32x16_bf16 v[2:17], v[94:97], v[98:101], 0
	s_waitcnt vmcnt(4)
	ds_write_b128 v142, v[82:85] offset:55296
	ds_read_b128 v[102:105], v168 offset:18496
	ds_read_b128 v[94:97], v168 offset:23104
	ds_read_b128 v[106:109], v169 offset:64
	ds_read_b128 v[98:101], v169 offset:4672
	s_waitcnt lgkmcnt(4)
	v_mfma_f32_32x32x16_bf16 v[50:65], v[172:175], v[180:183], v[50:65]
	s_waitcnt vmcnt(3)
	ds_write_b128 v144, v[78:81] offset:36864
	v_mfma_f32_32x32x16_bf16 v[34:49], v[176:179], v[180:183], v[34:49]
	s_waitcnt vmcnt(2)
	ds_write_b128 v144, v[86:89] offset:55296
	v_mfma_f32_32x32x16_bf16 v[18:33], v[172:175], v[184:187], v[18:33]
	s_waitcnt vmcnt(1)
	ds_write_b128 v146, v[90:93] offset:36864
	v_mfma_f32_32x32x16_bf16 v[2:17], v[176:179], v[184:187], v[2:17]
	s_waitcnt vmcnt(0)
	ds_write_b128 v146, v[110:113] offset:55296
	ds_read_b128 v[172:175], v168 offset:18528
	ds_read_b128 v[176:179], v168 offset:23136
	ds_read_b128 v[180:183], v169 offset:96
	ds_read_b128 v[184:187], v169 offset:4704
	s_waitcnt lgkmcnt(8)
	v_mfma_f32_32x32x16_bf16 v[50:65], v[102:105], v[106:109], v[50:65]
	s_mov_b64 exec, s[4:5]
	global_load_dwordx4 v[66:69], v224, s[64:65]
	s_mov_b64 exec, -1
	global_load_dwordx4 v[74:77], v220, s[64:65]
	v_mfma_f32_32x32x16_bf16 v[34:49], v[94:97], v[106:109], v[34:49]
	s_mov_b64 exec, s[6:7]
	global_load_dwordx4 v[70:73], v225, s[64:65]
	s_mov_b64 exec, -1
	global_load_dwordx4 v[82:85], v221, s[64:65]
	v_mfma_f32_32x32x16_bf16 v[18:33], v[102:105], v[98:101], v[18:33]
	s_mov_b64 exec, s[8:9]
	global_load_dwordx4 v[78:81], v226, s[64:65]
	s_mov_b64 exec, -1
	global_load_dwordx4 v[86:89], v222, s[64:65]
	v_mfma_f32_32x32x16_bf16 v[2:17], v[94:97], v[98:101], v[2:17]
	s_mov_b64 exec, s[10:11]
	global_load_dwordx4 v[90:93], v227, s[64:65]
	s_mov_b64 exec, -1
	global_load_dwordx4 v[110:113], v223, s[64:65]
	s_add_u32 s64, s64, 0x4000
	s_addc_u32 s65, s65, 0
	s_waitcnt lgkmcnt(0)
	s_barrier
	ds_read_b128 v[102:105], v168 offset:55296
	ds_read_b128 v[94:97], v168 offset:59904
	ds_read_b128 v[106:109], v169 offset:36864
	ds_read_b128 v[98:101], v169 offset:41472
	v_mfma_f32_32x32x16_bf16 v[50:65], v[172:175], v[180:183], v[50:65]
	v_mfma_f32_32x32x16_bf16 v[34:49], v[176:179], v[180:183], v[34:49]
	v_mfma_f32_32x32x16_bf16 v[18:33], v[172:175], v[184:187], v[18:33]
	v_mfma_f32_32x32x16_bf16 v[2:17], v[176:179], v[184:187], v[2:17]
	ds_read_b128 v[172:175], v168 offset:55328
	ds_read_b128 v[176:179], v168 offset:59936
	ds_read_b128 v[180:183], v169 offset:36896
	ds_read_b128 v[184:187], v169 offset:41504
	s_waitcnt lgkmcnt(4)
	v_mfma_f32_32x32x16_bf16 v[50:65], v[102:105], v[106:109], v[50:65]
	s_waitcnt vmcnt(7)
	ds_write_b128 v140, v[66:69]
	v_mfma_f32_32x32x16_bf16 v[34:49], v[94:97], v[106:109], v[34:49]
	s_waitcnt vmcnt(6)
	ds_write_b128 v140, v[74:77] offset:18432
	v_mfma_f32_32x32x16_bf16 v[18:33], v[102:105], v[98:101], v[18:33]
	s_waitcnt vmcnt(5)
	ds_write_b128 v142, v[70:73]
	v_mfma_f32_32x32x16_bf16 v[2:17], v[94:97], v[98:101], v[2:17]
	s_waitcnt vmcnt(4)
	ds_write_b128 v142, v[82:85] offset:18432
	ds_read_b128 v[102:105], v168 offset:55360
	ds_read_b128 v[94:97], v168 offset:59968
	ds_read_b128 v[106:109], v169 offset:36928
	ds_read_b128 v[98:101], v169 offset:41536
	s_waitcnt lgkmcnt(4)
	v_mfma_f32_32x32x16_bf16 v[50:65], v[172:175], v[180:183], v[50:65]
	s_waitcnt vmcnt(3)
	ds_write_b128 v144, v[78:81]
	v_mfma_f32_32x32x16_bf16 v[34:49], v[176:179], v[180:183], v[34:49]
	s_waitcnt vmcnt(2)
	ds_write_b128 v144, v[86:89] offset:18432
	v_mfma_f32_32x32x16_bf16 v[18:33], v[172:175], v[184:187], v[18:33]
	s_waitcnt vmcnt(1)
	ds_write_b128 v146, v[90:93]
	v_mfma_f32_32x32x16_bf16 v[2:17], v[176:179], v[184:187], v[2:17]
	s_waitcnt vmcnt(0)
	ds_write_b128 v146, v[110:113] offset:18432
	ds_read_b128 v[172:175], v168 offset:55392
	ds_read_b128 v[176:179], v168 offset:60000
	ds_read_b128 v[180:183], v169 offset:36960
	ds_read_b128 v[184:187], v169 offset:41568
	s_waitcnt lgkmcnt(8)
	v_mfma_f32_32x32x16_bf16 v[50:65], v[102:105], v[106:109], v[50:65]
	s_mov_b64 exec, s[4:5]
	global_load_dwordx4 v[66:69], v224, s[64:65]
	s_mov_b64 exec, -1
	global_load_dwordx4 v[74:77], v220, s[64:65]
	v_mfma_f32_32x32x16_bf16 v[34:49], v[94:97], v[106:109], v[34:49]
	s_mov_b64 exec, s[6:7]
	global_load_dwordx4 v[70:73], v225, s[64:65]
	s_mov_b64 exec, -1
	global_load_dwordx4 v[82:85], v221, s[64:65]
	v_mfma_f32_32x32x16_bf16 v[18:33], v[102:105], v[98:101], v[18:33]
	s_mov_b64 exec, s[8:9]
	global_load_dwordx4 v[78:81], v226, s[64:65]
	s_mov_b64 exec, -1
	global_load_dwordx4 v[86:89], v222, s[64:65]
	v_mfma_f32_32x32x16_bf16 v[2:17], v[94:97], v[98:101], v[2:17]
	s_mov_b64 exec, s[10:11]
	global_load_dwordx4 v[90:93], v227, s[64:65]
	s_mov_b64 exec, -1
	global_load_dwordx4 v[110:113], v223, s[64:65]
	s_add_u32 s64, s64, 0x4000
	s_addc_u32 s65, s65, 0
	s_waitcnt lgkmcnt(0)
	s_barrier
	ds_read_b128 v[102:105], v168 offset:18432
	ds_read_b128 v[94:97], v168 offset:23040
	ds_read_b128 v[106:109], v169
	ds_read_b128 v[98:101], v169 offset:4608
	v_mfma_f32_32x32x16_bf16 v[50:65], v[172:175], v[180:183], v[50:65]
	v_mfma_f32_32x32x16_bf16 v[34:49], v[176:179], v[180:183], v[34:49]
	v_mfma_f32_32x32x16_bf16 v[18:33], v[172:175], v[184:187], v[18:33]
	v_mfma_f32_32x32x16_bf16 v[2:17], v[176:179], v[184:187], v[2:17]
